# scan chunk loop: A-fragment ds_reads software-prefetched 10 fragments ahead into spare VGPRs with counted lgkmcnt waits
# baseline (speedup 1.0000x reference)
.LBB0_1296:
	s_add_i32 s0, s25, s13
	s_mul_hi_i32 s29, s0, 0x16800
	s_mul_i32 s0, s0, 0x16800
	s_add_u32 s30, s16, s0
	s_addc_u32 s31, s17, s29
	s_bitcmp1_b32 s13, 0
	s_cselect_b32 s0, 0xe000, 0
	s_add_i32 s13, s13, 1
	s_add_u32 s34, s30, s14
	s_addc_u32 s35, s31, s15
	s_bitcmp1_b32 s13, 0
	s_waitcnt vmcnt(16)
	v_mov_b64_e32 v[52:53], v[36:37]
	s_cselect_b32 s29, 0xe000, 0
	v_mov_b64_e32 v[50:51], v[34:35]
	v_lshl_add_u64 v[34:35], s[34:35], 0, v[68:69]
	s_mov_b64 s[34:35], 0x16800
	s_add_i32 s29, s26, s29
	s_waitcnt vmcnt(16)
	s_barrier
	global_load_dword v82, v231, s[30:31]
	v_lshl_add_u64 v[36:37], v[34:35], 0, s[34:35]
	s_mov_b32 m0, s29
	s_mov_b64 s[34:35], 0x18800
	global_load_lds_dwordx4 v[36:37], off
	v_lshl_add_u64 v[36:37], v[34:35], 0, s[34:35]
	s_add_i32 m0, s29, 0x2000
	s_mov_b64 s[34:35], 0x1a800
	global_load_lds_dwordx4 v[36:37], off
	v_lshl_add_u64 v[36:37], v[34:35], 0, s[34:35]
	s_add_i32 m0, s29, 0x4000
	s_mov_b64 s[34:35], 0x1c800
	global_load_lds_dwordx4 v[36:37], off
	v_lshl_add_u64 v[36:37], v[34:35], 0, s[34:35]
	s_add_i32 m0, s29, 0x6000
	s_mov_b64 s[34:35], 0x1e800
	global_load_lds_dwordx4 v[36:37], off
	v_lshl_add_u64 v[36:37], v[34:35], 0, s[34:35]
	s_add_i32 m0, s29, 0x8000
	s_mov_b64 s[34:35], 0x20800
	global_load_lds_dwordx4 v[36:37], off
	v_lshl_add_u64 v[36:37], v[34:35], 0, s[34:35]
	s_add_i32 m0, s29, 0xa000
	s_mov_b64 s[34:35], 0x22800
	global_load_lds_dwordx4 v[36:37], off
	s_add_i32 m0, s29, 0xc000
	v_lshl_add_u64 v[34:35], v[34:35], 0, s[34:35]
	s_add_u32 s34, s30, 0x24800
	s_addc_u32 s35, s31, 0
	v_mov_b64_e32 v[64:65], v[48:49]
	global_load_lds_dwordx4 v[34:35], off
	v_lshl_add_u64 v[34:35], v[74:75], 2, s[34:35]
	v_mov_b64_e32 v[62:63], v[46:47]
	v_mov_b64_e32 v[60:61], v[44:45]
	global_load_dwordx4 v[46:49], v[34:35], off
	v_lshl_add_u64 v[34:35], v[76:77], 2, s[34:35]
	v_mov_b64_e32 v[58:59], v[42:43]
	v_mov_b64_e32 v[56:57], v[40:41]
	global_load_dwordx4 v[42:45], v[34:35], off
	v_lshl_add_u64 v[34:35], v[78:79], 2, s[34:35]
	v_mov_b64_e32 v[54:55], v[38:39]
	global_load_dwordx4 v[38:41], v[34:35], off
	v_lshl_add_u64 v[34:35], v[80:81], 2, s[34:35]
	v_add_u32_e32 v105, s0, v95
	global_load_dwordx4 v[34:37], v[34:35], off
	s_nop 0
	ds_read_b128 v[144:147], v105
	ds_read_b128 v[148:151], v105 offset:16384
	ds_read_b128 v[152:155], v105 offset:1024
	ds_read_b128 v[160:163], v105 offset:17408
	ds_read_b128 v[164:167], v105 offset:8192
	ds_read_b128 v[168:171], v105 offset:24576
	ds_read_b128 v[172:175], v105 offset:9216
	ds_read_b128 v[176:179], v105 offset:25600
	ds_read_b128 v[180:183], v105 offset:2048
	ds_read_b128 v[184:187], v105 offset:18432
	v_cvt_pk_bf16_f32 v106, v30, v31
	v_cvt_pk_bf16_f32 v107, v32, v33
	v_cvt_pk_bf16_f32 v108, v22, v23
	v_cvt_pk_bf16_f32 v109, v24, v25
	v_cvt_pk_bf16_f32 v110, v26, v27
	v_cvt_pk_bf16_f32 v111, v28, v29
	ds_read_b128 v[188:191], v105 offset:3072
	s_waitcnt lgkmcnt(10)
	v_mfma_f32_16x16x32_bf16 v[62:65], v[144:147], v[106:109], v[62:65]
	v_cvt_pk_bf16_f32 v112, v14, v15
	v_cvt_pk_bf16_f32 v113, v16, v17
	v_cvt_pk_bf16_f32 v114, v18, v19
	ds_read_b128 v[192:195], v105 offset:19456
	s_waitcnt lgkmcnt(10)
	v_mfma_f32_16x16x32_bf16 v[122:125], v[148:151], v[106:109], 0
	v_cvt_pk_bf16_f32 v115, v20, v21
	v_cvt_pk_bf16_f32 v116, v6, v7
	ds_read_b128 v[204:207], v105 offset:10240
	s_waitcnt lgkmcnt(10)
	v_mfma_f32_16x16x32_bf16 v[62:65], v[152:155], v[110:113], v[62:65]
	v_cvt_pk_bf16_f32 v117, v8, v9
	v_cvt_pk_bf16_f32 v118, v10, v11
	v_cvt_pk_bf16_f32 v119, v12, v13
	ds_read_b128 v[208:211], v105 offset:26624
	s_waitcnt lgkmcnt(10)
	v_mfma_f32_16x16x32_bf16 v[122:125], v[160:163], v[110:113], v[122:125]
	v_cvt_pk_bf16_f32 v120, v2, v3
	v_cvt_pk_bf16_f32 v121, v4, v5
	ds_read_b128 v[212:215], v105 offset:11264
	s_waitcnt lgkmcnt(10)
	v_mfma_f32_16x16x32_bf16 v[62:65], v[164:167], v[114:117], v[62:65]
	s_waitcnt vmcnt(11)
	v_pk_mul_f32 v[32:33], v[32:33], v[82:83] op_sel_hi:[1,0]
	ds_read_b128 v[216:219], v105 offset:27648
	s_waitcnt lgkmcnt(10)
	v_mfma_f32_16x16x32_bf16 v[122:125], v[168:171], v[114:117], v[122:125]
	v_pk_mul_f32 v[30:31], v[30:31], v[82:83] op_sel_hi:[1,0]
	v_pk_mul_f32 v[24:25], v[24:25], v[82:83] op_sel_hi:[1,0]
	ds_read_b128 v[144:147], v105 offset:4096
	s_waitcnt lgkmcnt(10)
	v_mfma_f32_16x16x32_bf16 v[62:65], v[172:175], v[118:121], v[62:65]
	v_mul_f32_e64 v22, v22, v82
	v_mul_f32_e64 v23, v23, v82
	v_pk_mul_f32 v[28:29], v[28:29], v[82:83] op_sel_hi:[1,0]
	v_pk_mul_f32 v[26:27], v[26:27], v[82:83] op_sel_hi:[1,0]
	ds_read_b128 v[148:151], v105 offset:20480
	s_waitcnt lgkmcnt(10)
	v_mfma_f32_16x16x32_bf16 v[122:125], v[176:179], v[118:121], v[122:125]
	v_pk_mul_f32 v[16:17], v[16:17], v[82:83] op_sel_hi:[1,0]
	v_pk_mul_f32 v[14:15], v[14:15], v[82:83] op_sel_hi:[1,0]
	ds_read_b128 v[152:155], v105 offset:5120
	s_waitcnt lgkmcnt(10)
	v_mfma_f32_16x16x32_bf16 v[58:61], v[180:183], v[106:109], v[58:61]
	v_mul_f32_e64 v20, v20, v82
	v_mul_f32_e64 v21, v21, v82
	v_pk_mul_f32 v[18:19], v[18:19], v[82:83] op_sel_hi:[1,0]
	v_pk_mul_f32 v[8:9], v[8:9], v[82:83] op_sel_hi:[1,0]
	ds_read_b128 v[160:163], v105 offset:21504
	s_waitcnt lgkmcnt(10)
	v_mfma_f32_16x16x32_bf16 v[126:129], v[184:187], v[106:109], 0
	v_pk_mul_f32 v[6:7], v[6:7], v[82:83] op_sel_hi:[1,0]
	v_pk_mul_f32 v[12:13], v[12:13], v[82:83] op_sel_hi:[1,0]
	ds_read_b128 v[164:167], v105 offset:12288
	s_waitcnt lgkmcnt(10)
	v_mfma_f32_16x16x32_bf16 v[58:61], v[188:191], v[110:113], v[58:61]
	v_mul_f32_e64 v10, v10, v82
	v_mul_f32_e64 v11, v11, v82
	v_pk_mul_f32 v[4:5], v[4:5], v[82:83] op_sel_hi:[1,0]
	v_pk_mul_f32 v[2:3], v[2:3], v[82:83] op_sel_hi:[1,0]
	ds_read_b128 v[168:171], v105 offset:28672
	s_waitcnt lgkmcnt(10)
	v_mfma_f32_16x16x32_bf16 v[126:129], v[192:195], v[110:113], v[126:129]
	v_add_u32_e32 v82, s27, v84
	s_add_i32 s27, s27, 64
	ds_read_b128 v[172:175], v105 offset:13312
	s_waitcnt lgkmcnt(10)
	v_mfma_f32_16x16x32_bf16 v[58:61], v[204:207], v[114:117], v[58:61]
	s_cmp_eq_u32 s28, s27
	ds_read_b128 v[176:179], v105 offset:29696
	s_waitcnt lgkmcnt(10)
	v_mfma_f32_16x16x32_bf16 v[126:129], v[208:211], v[114:117], v[126:129]
	ds_read_b128 v[180:183], v105 offset:6144
	s_waitcnt lgkmcnt(10)
	v_mfma_f32_16x16x32_bf16 v[58:61], v[212:215], v[118:121], v[58:61]
	ds_read_b128 v[184:187], v105 offset:22528
	s_waitcnt lgkmcnt(10)
	v_mfma_f32_16x16x32_bf16 v[126:129], v[216:219], v[118:121], v[126:129]
	ds_read_b128 v[188:191], v105 offset:7168
	s_waitcnt lgkmcnt(10)
	v_mfma_f32_16x16x32_bf16 v[54:57], v[144:147], v[106:109], v[54:57]
	ds_read_b128 v[192:195], v105 offset:23552
	s_waitcnt lgkmcnt(10)
	v_mfma_f32_16x16x32_bf16 v[130:133], v[148:151], v[106:109], 0
	ds_read_b128 v[204:207], v105 offset:14336
	s_waitcnt lgkmcnt(10)
	v_mfma_f32_16x16x32_bf16 v[54:57], v[152:155], v[110:113], v[54:57]
	ds_read_b128 v[208:211], v105 offset:30720
	s_waitcnt lgkmcnt(10)
	v_mfma_f32_16x16x32_bf16 v[130:133], v[160:163], v[110:113], v[130:133]
	ds_read_b128 v[212:215], v105 offset:15360
	s_waitcnt lgkmcnt(10)
	v_mfma_f32_16x16x32_bf16 v[54:57], v[164:167], v[114:117], v[54:57]
	ds_read_b128 v[216:219], v105 offset:31744
	s_waitcnt lgkmcnt(10)
	v_mfma_f32_16x16x32_bf16 v[130:133], v[168:171], v[114:117], v[130:133]
	ds_read_b128 v[144:147], v105 offset:49152
	s_waitcnt lgkmcnt(10)
	v_mfma_f32_16x16x32_bf16 v[54:57], v[172:175], v[118:121], v[54:57]
	ds_read_b128 v[148:151], v105 offset:50176
	s_waitcnt lgkmcnt(10)
	v_mfma_f32_16x16x32_bf16 v[130:133], v[176:179], v[118:121], v[130:133]
	ds_read_b128 v[152:155], v105 offset:51200
	s_waitcnt lgkmcnt(10)
	v_mfma_f32_16x16x32_bf16 v[50:53], v[180:183], v[106:109], v[50:53]
	ds_read_b128 v[160:163], v105 offset:52224
	s_waitcnt lgkmcnt(10)
	v_mfma_f32_16x16x32_bf16 v[106:109], v[184:187], v[106:109], 0
	ds_read_b128 v[164:167], v105 offset:53248
	s_waitcnt lgkmcnt(10)
	v_mfma_f32_16x16x32_bf16 v[50:53], v[188:191], v[110:113], v[50:53]
	ds_read_b128 v[168:171], v105 offset:54272
	s_waitcnt lgkmcnt(10)
	v_mfma_f32_16x16x32_bf16 v[106:109], v[192:195], v[110:113], v[106:109]
	ds_read_b128 v[172:175], v105 offset:55296
	s_waitcnt lgkmcnt(10)
	v_mfma_f32_16x16x32_bf16 v[50:53], v[204:207], v[114:117], v[50:53]
	ds_read_b128 v[176:179], v105 offset:56320
	s_waitcnt lgkmcnt(10)
	v_mfma_f32_16x16x32_bf16 v[106:109], v[208:211], v[114:117], v[106:109]
	ds_read_b128 v[180:183], v105 offset:32768
	s_waitcnt lgkmcnt(10)
	v_mfma_f32_16x16x32_bf16 v[50:53], v[212:215], v[118:121], v[50:53]
	v_cvt_pk_bf16_f32 v110, v62, v63
	v_cvt_pk_bf16_f32 v111, v64, v65
	v_cvt_pk_bf16_f32 v112, v58, v59
	ds_read_b128 v[184:187], v105 offset:33792
	s_waitcnt lgkmcnt(10)
	v_mfma_f32_16x16x32_bf16 v[106:109], v[216:219], v[118:121], v[106:109]
	s_nop 2
	v_cvt_pk_bf16_f32 v116, v50, v51
	v_cvt_pk_bf16_f32 v117, v52, v53
	v_cvt_pk_bf16_f32 v114, v54, v55
	v_cvt_pk_bf16_f32 v115, v56, v57
	v_cvt_pk_bf16_f32 v113, v60, v61
	s_nop 0
	ds_read_b128 v[188:191], v105 offset:34816
	s_waitcnt lgkmcnt(10)
	v_mfma_f32_16x16x32_bf16 v[50:53], v[144:147], v[110:113], v[122:125]
	ds_read_b128 v[192:195], v105 offset:35840
	s_waitcnt lgkmcnt(10)
	v_mfma_f32_16x16x32_bf16 v[62:65], v[148:151], v[114:117], v[50:53]
	ds_read_b128 v[204:207], v105 offset:36864
	s_waitcnt lgkmcnt(10)
	v_mfma_f32_16x16x32_bf16 v[50:53], v[152:155], v[110:113], v[126:129]
	ds_read_b128 v[208:211], v105 offset:37888
	s_waitcnt lgkmcnt(10)
	v_mfma_f32_16x16x32_bf16 v[58:61], v[160:163], v[114:117], v[50:53]
	ds_read_b128 v[212:215], v105 offset:38912
	s_waitcnt lgkmcnt(10)
	v_mfma_f32_16x16x32_bf16 v[50:53], v[164:167], v[110:113], v[130:133]
	ds_read_b128 v[216:219], v105 offset:39936
	s_waitcnt lgkmcnt(10)
	v_mfma_f32_16x16x32_bf16 v[54:57], v[168:171], v[114:117], v[50:53]
	ds_read_b128 v[144:147], v105 offset:40960
	s_waitcnt lgkmcnt(10)
	v_mfma_f32_16x16x32_bf16 v[50:53], v[172:175], v[110:113], v[106:109]
	ds_read_b128 v[148:151], v105 offset:41984
	s_waitcnt lgkmcnt(10)
	v_mfma_f32_16x16x32_bf16 v[50:53], v[176:179], v[114:117], v[50:53]
	ds_read_b128 v[152:155], v105 offset:43008
	s_waitcnt lgkmcnt(10)
	v_mfma_f32_16x16x32_bf16 v[30:33], v[180:183], v[110:113], v[30:33]
	ds_read_b128 v[160:163], v105 offset:44032
	s_waitcnt lgkmcnt(10)
	v_mfma_f32_16x16x32_bf16 v[30:33], v[184:187], v[114:117], v[30:33]
	ds_read_b128 v[164:167], v105 offset:45056
	s_waitcnt lgkmcnt(10)
	v_mfma_f32_16x16x32_bf16 v[22:25], v[188:191], v[110:113], v[22:25]
	ds_read_b128 v[168:171], v105 offset:46080
	s_waitcnt lgkmcnt(10)
	v_mfma_f32_16x16x32_bf16 v[22:25], v[192:195], v[114:117], v[22:25]
	ds_read_b128 v[172:175], v105 offset:47104
	s_waitcnt lgkmcnt(10)
	v_mfma_f32_16x16x32_bf16 v[26:29], v[204:207], v[110:113], v[26:29]
	ds_read_b128 v[176:179], v105 offset:48128
	s_waitcnt lgkmcnt(10)
	v_mfma_f32_16x16x32_bf16 v[26:29], v[208:211], v[114:117], v[26:29]
	s_waitcnt lgkmcnt(9)
	v_mfma_f32_16x16x32_bf16 v[14:17], v[212:215], v[110:113], v[14:17]
	s_waitcnt lgkmcnt(8)
	v_mfma_f32_16x16x32_bf16 v[14:17], v[216:219], v[114:117], v[14:17]
	s_waitcnt lgkmcnt(7)
	v_mfma_f32_16x16x32_bf16 v[18:21], v[144:147], v[110:113], v[18:21]
	s_waitcnt lgkmcnt(6)
	v_mfma_f32_16x16x32_bf16 v[18:21], v[148:151], v[114:117], v[18:21]
	s_waitcnt lgkmcnt(5)
	v_mfma_f32_16x16x32_bf16 v[6:9], v[152:155], v[110:113], v[6:9]
	s_waitcnt lgkmcnt(4)
	v_mfma_f32_16x16x32_bf16 v[6:9], v[160:163], v[114:117], v[6:9]
	s_waitcnt lgkmcnt(3)
	v_mfma_f32_16x16x32_bf16 v[10:13], v[164:167], v[110:113], v[10:13]
	s_waitcnt lgkmcnt(2)
	v_mfma_f32_16x16x32_bf16 v[10:13], v[168:171], v[114:117], v[10:13]
	s_waitcnt lgkmcnt(1)
	v_mfma_f32_16x16x32_bf16 v[2:5], v[172:175], v[110:113], v[2:5]
	v_add3_u32 v105, s28, v104, 63
	v_cndmask_b32_e32 v105, v105, v82, vcc
	s_waitcnt lgkmcnt(0)
	v_mfma_f32_16x16x32_bf16 v[2:5], v[176:179], v[114:117], v[2:5]
	v_add_u32_e32 v106, s24, v105
	v_ashrrev_i32_e32 v107, 31, v106
	v_lshlrev_b64 v[106:107], 11, v[106:107]
	v_lshl_add_u64 v[106:107], v[72:73], 0, v[106:107]
	global_store_dword v[106:107], v62, off
	v_add_u32_e32 v62, 1, v82
	v_xad_u32 v105, v82, -2, s12
	v_cndmask_b32_e32 v62, v105, v62, vcc
	v_add_u32_e32 v106, s24, v62
	v_ashrrev_i32_e32 v107, 31, v106
	v_lshlrev_b64 v[106:107], 11, v[106:107]
	v_lshl_add_u64 v[106:107], v[72:73], 0, v[106:107]
	global_store_dword v[106:107], v63, off
	v_add_u32_e32 v62, 2, v82
	v_xad_u32 v63, v82, -3, s12
	v_cndmask_b32_e32 v62, v63, v62, vcc
	v_add_u32_e32 v62, s24, v62
	v_ashrrev_i32_e32 v63, 31, v62
	v_lshlrev_b64 v[62:63], 11, v[62:63]
	v_lshl_add_u64 v[62:63], v[72:73], 0, v[62:63]
	global_store_dword v[62:63], v64, off
	v_add_u32_e32 v62, 3, v82
	v_xad_u32 v63, v82, -4, s12
	v_cndmask_b32_e32 v62, v63, v62, vcc
	v_add_u32_e32 v62, s24, v62
	v_ashrrev_i32_e32 v63, 31, v62
	v_lshlrev_b64 v[62:63], 11, v[62:63]
	v_lshl_add_u64 v[62:63], v[72:73], 0, v[62:63]
	global_store_dword v[62:63], v65, off
	v_xor_b32_e32 v63, 0xffffffef, v82
	v_add_u32_e32 v62, 16, v82
	v_add_u32_e32 v63, s12, v63
	v_cndmask_b32_e32 v62, v63, v62, vcc
	v_add_u32_e32 v62, s24, v62
	v_ashrrev_i32_e32 v63, 31, v62
	v_lshlrev_b64 v[62:63], 11, v[62:63]
	v_lshl_add_u64 v[62:63], v[72:73], 0, v[62:63]
	global_store_dword v[62:63], v58, off
	v_xor_b32_e32 v62, 0xffffffee, v82
	v_add_u32_e32 v58, 17, v82
	v_add_u32_e32 v62, s12, v62
	v_cndmask_b32_e32 v58, v62, v58, vcc
	v_add_u32_e32 v62, s24, v58
	v_ashrrev_i32_e32 v63, 31, v62
	v_lshlrev_b64 v[62:63], 11, v[62:63]
	v_lshl_add_u64 v[62:63], v[72:73], 0, v[62:63]
	global_store_dword v[62:63], v59, off
	v_xor_b32_e32 v59, 0xffffffed, v82
	v_add_u32_e32 v58, 18, v82
	v_add_u32_e32 v59, s12, v59
	v_cndmask_b32_e32 v58, v59, v58, vcc
	v_add_u32_e32 v58, s24, v58
	v_ashrrev_i32_e32 v59, 31, v58
	v_lshlrev_b64 v[58:59], 11, v[58:59]
	v_lshl_add_u64 v[58:59], v[72:73], 0, v[58:59]
	global_store_dword v[58:59], v60, off
	v_xor_b32_e32 v59, 0xffffffec, v82
	v_add_u32_e32 v58, 19, v82
	v_add_u32_e32 v59, s12, v59
	v_cndmask_b32_e32 v58, v59, v58, vcc
	v_add_u32_e32 v58, s24, v58
	v_ashrrev_i32_e32 v59, 31, v58
	v_lshlrev_b64 v[58:59], 11, v[58:59]
	v_lshl_add_u64 v[58:59], v[72:73], 0, v[58:59]
	global_store_dword v[58:59], v61, off
	v_xor_b32_e32 v59, 0xffffffdf, v82
	v_add_u32_e32 v58, 32, v82
	v_add_u32_e32 v59, s12, v59
	v_cndmask_b32_e32 v58, v59, v58, vcc
	v_add_u32_e32 v58, s24, v58
	v_ashrrev_i32_e32 v59, 31, v58
	v_lshlrev_b64 v[58:59], 11, v[58:59]
	v_lshl_add_u64 v[58:59], v[72:73], 0, v[58:59]
	global_store_dword v[58:59], v54, off
	v_xor_b32_e32 v58, 0xffffffde, v82
	v_add_u32_e32 v54, 33, v82
	v_add_u32_e32 v58, s12, v58
	v_cndmask_b32_e32 v54, v58, v54, vcc
	v_add_u32_e32 v58, s24, v54
	v_ashrrev_i32_e32 v59, 31, v58
	v_lshlrev_b64 v[58:59], 11, v[58:59]
	v_lshl_add_u64 v[58:59], v[72:73], 0, v[58:59]
	global_store_dword v[58:59], v55, off
	v_xor_b32_e32 v55, 0xffffffdd, v82
	v_add_u32_e32 v54, 34, v82
	v_add_u32_e32 v55, s12, v55
	v_cndmask_b32_e32 v54, v55, v54, vcc
	v_add_u32_e32 v54, s24, v54
	v_ashrrev_i32_e32 v55, 31, v54
	v_lshlrev_b64 v[54:55], 11, v[54:55]
	v_lshl_add_u64 v[54:55], v[72:73], 0, v[54:55]
	global_store_dword v[54:55], v56, off
	v_xor_b32_e32 v55, 0xffffffdc, v82
	v_add_u32_e32 v54, 35, v82
	v_add_u32_e32 v55, s12, v55
	v_cndmask_b32_e32 v54, v55, v54, vcc
	v_add_u32_e32 v54, s24, v54
	v_ashrrev_i32_e32 v55, 31, v54
	v_lshlrev_b64 v[54:55], 11, v[54:55]
	v_lshl_add_u64 v[54:55], v[72:73], 0, v[54:55]
	global_store_dword v[54:55], v57, off
	v_xor_b32_e32 v55, 0xffffffcf, v82
	v_add_u32_e32 v54, 48, v82
	v_add_u32_e32 v55, s12, v55
	v_cndmask_b32_e32 v54, v55, v54, vcc
	v_add_u32_e32 v54, s24, v54
	v_ashrrev_i32_e32 v55, 31, v54
	v_lshlrev_b64 v[54:55], 11, v[54:55]
	v_lshl_add_u64 v[54:55], v[72:73], 0, v[54:55]
	global_store_dword v[54:55], v50, off
	v_xor_b32_e32 v54, 0xffffffce, v82
	v_add_u32_e32 v50, 49, v82
	v_add_u32_e32 v54, s12, v54
	v_cndmask_b32_e32 v50, v54, v50, vcc
	v_add_u32_e32 v54, s24, v50
	v_ashrrev_i32_e32 v55, 31, v54
	v_lshlrev_b64 v[54:55], 11, v[54:55]
	v_lshl_add_u64 v[54:55], v[72:73], 0, v[54:55]
	global_store_dword v[54:55], v51, off
	v_xor_b32_e32 v51, 0xffffffcd, v82
	v_add_u32_e32 v50, 50, v82
	v_add_u32_e32 v51, s12, v51
	v_cndmask_b32_e32 v50, v51, v50, vcc
	v_add_u32_e32 v50, s24, v50
	v_ashrrev_i32_e32 v51, 31, v50
	v_lshlrev_b64 v[50:51], 11, v[50:51]
	v_lshl_add_u64 v[50:51], v[72:73], 0, v[50:51]
	global_store_dword v[50:51], v52, off
	v_xor_b32_e32 v51, 0xffffffcc, v82
	v_add_u32_e32 v50, 51, v82
	v_add_u32_e32 v51, s12, v51
	v_cndmask_b32_e32 v50, v51, v50, vcc
	v_add_u32_e32 v50, s24, v50
	v_ashrrev_i32_e32 v51, 31, v50
	v_lshlrev_b64 v[50:51], 11, v[50:51]
	v_lshl_add_u64 v[50:51], v[72:73], 0, v[50:51]
	v_subrev_u32_e32 v104, 64, v104
	global_store_dword v[50:51], v53, off
	s_cbranch_scc0 .LBB0_1296
	s_waitcnt vmcnt(0)
	s_barrier
	v_add_u32_e32 v75, s20, v86
	ds_read_b128 v[76:79], v95 offset:57344
	ds_read_b128 v[104:107], v75
	s_add_i32 s0, s13, s25
	s_mul_hi_i32 s15, s0, 0x16800
	s_mul_i32 s0, s0, 0x16800
	s_add_u32 s14, s16, s0
	s_addc_u32 s15, s17, s15
	v_cvt_pk_bf16_f32 v62, v30, v31
	v_cvt_pk_bf16_f32 v63, v32, v33
	v_cvt_pk_bf16_f32 v64, v22, v23
	v_cvt_pk_bf16_f32 v65, v24, v25
	global_load_dword v74, v231, s[14:15]
	v_cvt_pk_bf16_f32 v58, v26, v27
	s_waitcnt lgkmcnt(1)
	v_mfma_f32_16x16x32_bf16 v[46:49], v[76:79], v[62:65], v[46:49]
	v_cvt_pk_bf16_f32 v59, v28, v29
	v_cvt_pk_bf16_f32 v60, v14, v15
	v_cvt_pk_bf16_f32 v61, v16, v17
	s_waitcnt lgkmcnt(0)
	v_mfma_f32_16x16x32_bf16 v[76:79], v[104:107], v[62:65], 0
	ds_read_b128 v[104:107], v95 offset:58368
	ds_read_b128 v[108:111], v97
	v_add_u32_e32 v75, s2, v87
	v_cvt_pk_bf16_f32 v54, v18, v19
	s_waitcnt lgkmcnt(1)
	v_mfma_f32_16x16x32_bf16 v[46:49], v[104:107], v[58:61], v[46:49]
	ds_read_b128 v[104:107], v75 offset:57344
	v_add_u32_e32 v75, s20, v87
	v_cvt_pk_bf16_f32 v55, v20, v21
	s_waitcnt lgkmcnt(1)
	v_mfma_f32_16x16x32_bf16 v[76:79], v[108:111], v[58:61], v[76:79]
	ds_read_b128 v[108:111], v75
	v_cvt_pk_bf16_f32 v56, v6, v7
	v_cvt_pk_bf16_f32 v57, v8, v9
	v_add_u32_e32 v75, s2, v88
	v_cvt_pk_bf16_f32 v50, v10, v11
	s_waitcnt lgkmcnt(1)
	v_mfma_f32_16x16x32_bf16 v[46:49], v[104:107], v[54:57], v[46:49]
	ds_read_b128 v[104:107], v75 offset:57344
	v_add_u32_e32 v75, s20, v88
	v_cvt_pk_bf16_f32 v51, v12, v13
	s_waitcnt lgkmcnt(1)
	v_mfma_f32_16x16x32_bf16 v[76:79], v[108:111], v[54:57], v[76:79]
	ds_read_b128 v[108:111], v75
	v_cvt_pk_bf16_f32 v52, v2, v3
	v_cvt_pk_bf16_f32 v53, v4, v5
	v_add_u32_e32 v75, s2, v89
	s_lshl_b32 s0, s13, 6
	s_waitcnt lgkmcnt(1)
	v_mfma_f32_16x16x32_bf16 v[104:107], v[104:107], v[50:53], v[46:49]
	s_waitcnt lgkmcnt(0)
	v_mfma_f32_16x16x32_bf16 v[46:49], v[108:111], v[50:53], v[76:79]
	s_nop 2
	ds_read_b128 v[76:79], v95 offset:59392
	ds_read_b128 v[108:111], v98
	s_waitcnt lgkmcnt(1)
	v_mfma_f32_16x16x32_bf16 v[42:45], v[76:79], v[62:65], v[42:45]
	s_waitcnt lgkmcnt(0)
	v_mfma_f32_16x16x32_bf16 v[76:79], v[108:111], v[62:65], 0
	ds_read_b128 v[108:111], v95 offset:60416
	ds_read_b128 v[112:115], v99
	s_waitcnt lgkmcnt(1)
	v_mfma_f32_16x16x32_bf16 v[42:45], v[108:111], v[58:61], v[42:45]
	ds_read_b128 v[108:111], v75 offset:57344
	v_add_u32_e32 v75, s20, v89
	s_waitcnt lgkmcnt(1)
	v_mfma_f32_16x16x32_bf16 v[76:79], v[112:115], v[58:61], v[76:79]
	ds_read_b128 v[112:115], v75
	v_add_u32_e32 v75, s2, v90
	s_waitcnt lgkmcnt(1)
	v_mfma_f32_16x16x32_bf16 v[42:45], v[108:111], v[54:57], v[42:45]
	ds_read_b128 v[108:111], v75 offset:57344
	v_add_u32_e32 v75, s20, v90
	s_waitcnt lgkmcnt(1)
	v_mfma_f32_16x16x32_bf16 v[76:79], v[112:115], v[54:57], v[76:79]
	ds_read_b128 v[112:115], v75
	v_add_u32_e32 v75, s2, v91
	s_waitcnt lgkmcnt(1)
	v_mfma_f32_16x16x32_bf16 v[42:45], v[108:111], v[50:53], v[42:45]
	s_waitcnt lgkmcnt(0)
	v_mfma_f32_16x16x32_bf16 v[76:79], v[112:115], v[50:53], v[76:79]
	ds_read_b128 v[108:111], v95 offset:61440
	ds_read_b128 v[112:115], v100
	s_waitcnt lgkmcnt(1)
	v_mfma_f32_16x16x32_bf16 v[38:41], v[108:111], v[62:65], v[38:41]
	s_waitcnt lgkmcnt(0)
	v_mfma_f32_16x16x32_bf16 v[108:111], v[112:115], v[62:65], 0
	ds_read_b128 v[112:115], v95 offset:62464
	ds_read_b128 v[116:119], v101
	s_waitcnt lgkmcnt(1)
	v_mfma_f32_16x16x32_bf16 v[38:41], v[112:115], v[58:61], v[38:41]
	ds_read_b128 v[112:115], v75 offset:57344
	v_add_u32_e32 v75, s20, v91
	s_waitcnt lgkmcnt(1)
	v_mfma_f32_16x16x32_bf16 v[108:111], v[116:119], v[58:61], v[108:111]
	ds_read_b128 v[116:119], v75
	v_add_u32_e32 v75, s2, v92
	s_waitcnt lgkmcnt(1)
	v_mfma_f32_16x16x32_bf16 v[38:41], v[112:115], v[54:57], v[38:41]
	ds_read_b128 v[112:115], v75 offset:57344
	v_add_u32_e32 v75, s20, v92
	s_waitcnt lgkmcnt(1)
	v_mfma_f32_16x16x32_bf16 v[108:111], v[116:119], v[54:57], v[108:111]
	ds_read_b128 v[116:119], v75
	v_add_u32_e32 v75, s20, v93
	s_waitcnt vmcnt(0)
	v_pk_mul_f32 v[32:33], v[32:33], v[74:75] op_sel_hi:[1,0]
	s_waitcnt lgkmcnt(1)
	v_mfma_f32_16x16x32_bf16 v[38:41], v[112:115], v[50:53], v[38:41]
	v_mul_f32_e64 v30, v30, v74
	v_mul_f32_e64 v31, v31, v74
	v_pk_mul_f32 v[24:25], v[24:25], v[74:75] op_sel_hi:[1,0]
	v_pk_mul_f32 v[22:23], v[22:23], v[74:75] op_sel_hi:[1,0]
	s_waitcnt lgkmcnt(0)
	v_mfma_f32_16x16x32_bf16 v[108:111], v[116:119], v[50:53], v[108:111]
	ds_read_b128 v[112:115], v95 offset:63488
	ds_read_b128 v[116:119], v102
	v_pk_mul_f32 v[28:29], v[28:29], v[74:75] op_sel_hi:[1,0]
	v_pk_mul_f32 v[26:27], v[26:27], v[74:75] op_sel_hi:[1,0]
	s_waitcnt lgkmcnt(1)
	v_mfma_f32_16x16x32_bf16 v[34:37], v[112:115], v[62:65], v[34:37]
	v_mul_f32_e64 v16, v16, v74
	v_mul_f32_e64 v17, v17, v74
	v_pk_mul_f32 v[14:15], v[14:15], v[74:75] op_sel_hi:[1,0]
	v_pk_mul_f32 v[20:21], v[20:21], v[74:75] op_sel_hi:[1,0]
	s_waitcnt lgkmcnt(0)
	v_mfma_f32_16x16x32_bf16 v[62:65], v[116:119], v[62:65], 0
	ds_read_b128 v[112:115], v95 offset:64512
	ds_read_b128 v[116:119], v103
	v_pk_mul_f32 v[18:19], v[18:19], v[74:75] op_sel_hi:[1,0]
	v_pk_mul_f32 v[8:9], v[8:9], v[74:75] op_sel_hi:[1,0]
	s_waitcnt lgkmcnt(1)
	v_mfma_f32_16x16x32_bf16 v[34:37], v[112:115], v[58:61], v[34:37]
	ds_read_b128 v[112:115], v75
	v_pk_mul_f32 v[6:7], v[6:7], v[74:75] op_sel_hi:[1,0]
	v_pk_mul_f32 v[12:13], v[12:13], v[74:75] op_sel_hi:[1,0]
	s_waitcnt lgkmcnt(1)
	v_mfma_f32_16x16x32_bf16 v[58:61], v[116:119], v[58:61], v[62:65]
	v_mul_f32_e64 v10, v10, v74
	v_mul_f32_e64 v11, v11, v74
	v_pk_mul_f32 v[4:5], v[4:5], v[74:75] op_sel_hi:[1,0]
	v_pk_mul_f32 v[2:3], v[2:3], v[74:75] op_sel_hi:[1,0]
	v_add_u32_e32 v62, s2, v93
	ds_read_b128 v[62:65], v62 offset:57344
	s_waitcnt lgkmcnt(0)
	v_mfma_f32_16x16x32_bf16 v[34:37], v[62:65], v[54:57], v[34:37]
	v_add_u32_e32 v62, s20, v94
	ds_read_b128 v[62:65], v62
	v_mfma_f32_16x16x32_bf16 v[54:57], v[112:115], v[54:57], v[58:61]
	s_nop 2
	v_add_u32_e32 v58, s2, v94
	ds_read_b128 v[58:61], v58 offset:57344
	s_waitcnt lgkmcnt(1)
	v_mfma_f32_16x16x32_bf16 v[54:57], v[62:65], v[50:53], v[54:57]
	v_add_u32_e32 v62, s21, v86
	s_waitcnt lgkmcnt(0)
	v_mfma_f32_16x16x32_bf16 v[34:37], v[58:61], v[50:53], v[34:37]
	v_cvt_pk_bf16_f32 v58, v38, v39
	v_cvt_pk_bf16_f32 v59, v40, v41
	ds_read_b128 v[38:41], v62 offset:1024
	s_nop 4
	v_cvt_pk_bf16_f32 v60, v34, v35
	v_cvt_pk_bf16_f32 v61, v36, v37
	ds_read_b128 v[34:37], v62
	v_cvt_pk_bf16_f32 v50, v104, v105
	v_cvt_pk_bf16_f32 v51, v106, v107
	v_cvt_pk_bf16_f32 v52, v42, v43
	v_cvt_pk_bf16_f32 v53, v44, v45
	s_waitcnt lgkmcnt(0)
	s_nop 0
	v_mfma_f32_16x16x32_bf16 v[34:37], v[34:37], v[50:53], v[46:49]
	v_mfma_f32_16x16x32_bf16 v[46:49], v[38:41], v[58:61], v[34:37]
	ds_read_b128 v[38:41], v62 offset:3072
	s_nop 5
	ds_read_b128 v[34:37], v62 offset:2048
	s_waitcnt lgkmcnt(0)
	v_mfma_f32_16x16x32_bf16 v[34:37], v[34:37], v[50:53], v[76:79]
	v_mfma_f32_16x16x32_bf16 v[42:45], v[38:41], v[58:61], v[34:37]
	ds_read_b128 v[38:41], v62 offset:5120
	s_nop 5
	ds_read_b128 v[34:37], v62 offset:4096
	s_waitcnt lgkmcnt(0)
	v_mfma_f32_16x16x32_bf16 v[34:37], v[34:37], v[50:53], v[108:111]
	v_mfma_f32_16x16x32_bf16 v[38:41], v[38:41], v[58:61], v[34:37]
	s_nop 6
	ds_read_b128 v[34:37], v62 offset:6144
	s_waitcnt lgkmcnt(0)
	v_mfma_f32_16x16x32_bf16 v[34:37], v[34:37], v[50:53], v[54:57]
	s_nop 2
	ds_read_b128 v[54:57], v62 offset:7168
	v_add_u32_e32 v62, s22, v86
	s_waitcnt lgkmcnt(0)
	v_mfma_f32_16x16x32_bf16 v[34:37], v[54:57], v[58:61], v[34:37]
	ds_read_b128 v[54:57], v62
	s_waitcnt lgkmcnt(0)
	v_mfma_f32_16x16x32_bf16 v[30:33], v[54:57], v[50:53], v[30:33]
	ds_read_b128 v[54:57], v62 offset:1024
	s_waitcnt lgkmcnt(0)
	v_mfma_f32_16x16x32_bf16 v[30:33], v[54:57], v[58:61], v[30:33]
	ds_read_b128 v[54:57], v62 offset:2048
	s_waitcnt lgkmcnt(0)
	v_mfma_f32_16x16x32_bf16 v[22:25], v[54:57], v[50:53], v[22:25]
	ds_read_b128 v[54:57], v62 offset:3072
	s_waitcnt lgkmcnt(0)
	v_mfma_f32_16x16x32_bf16 v[22:25], v[54:57], v[58:61], v[22:25]
	ds_read_b128 v[54:57], v62 offset:4096
	s_waitcnt lgkmcnt(0)
	v_mfma_f32_16x16x32_bf16 v[26:29], v[54:57], v[50:53], v[26:29]
	ds_read_b128 v[54:57], v62 offset:5120
	s_waitcnt lgkmcnt(0)
	v_mfma_f32_16x16x32_bf16 v[26:29], v[54:57], v[58:61], v[26:29]
	ds_read_b128 v[54:57], v62 offset:6144
	s_waitcnt lgkmcnt(0)
	v_mfma_f32_16x16x32_bf16 v[14:17], v[54:57], v[50:53], v[14:17]
	ds_read_b128 v[54:57], v62 offset:7168
	s_waitcnt lgkmcnt(0)
	v_mfma_f32_16x16x32_bf16 v[14:17], v[54:57], v[58:61], v[14:17]
	ds_read_b128 v[54:57], v62 offset:8192
	s_waitcnt lgkmcnt(0)
	v_mfma_f32_16x16x32_bf16 v[18:21], v[54:57], v[50:53], v[18:21]
	ds_read_b128 v[54:57], v62 offset:9216
	s_waitcnt lgkmcnt(0)
	v_mfma_f32_16x16x32_bf16 v[18:21], v[54:57], v[58:61], v[18:21]
	ds_read_b128 v[54:57], v62 offset:10240
	s_waitcnt lgkmcnt(0)
	v_mfma_f32_16x16x32_bf16 v[6:9], v[54:57], v[50:53], v[6:9]
	ds_read_b128 v[54:57], v62 offset:11264
	s_waitcnt lgkmcnt(0)
	v_mfma_f32_16x16x32_bf16 v[6:9], v[54:57], v[58:61], v[6:9]
	ds_read_b128 v[54:57], v62 offset:12288
	s_waitcnt lgkmcnt(0)
	v_mfma_f32_16x16x32_bf16 v[10:13], v[54:57], v[50:53], v[10:13]
	ds_read_b128 v[54:57], v62 offset:13312
	s_waitcnt lgkmcnt(0)
	v_mfma_f32_16x16x32_bf16 v[10:13], v[54:57], v[58:61], v[10:13]
	ds_read_b128 v[54:57], v62 offset:14336
	s_waitcnt lgkmcnt(0)
	v_mfma_f32_16x16x32_bf16 v[2:5], v[54:57], v[50:53], v[2:5]
	ds_read_b128 v[50:53], v62 offset:15360
	s_waitcnt lgkmcnt(0)
	v_mfma_f32_16x16x32_bf16 v[2:5], v[50:53], v[58:61], v[2:5]
	v_or_b32_e32 v52, s0, v84
	v_xad_u32 v50, v52, -1, s12
	v_cndmask_b32_e32 v50, v50, v52, vcc
	v_add_u32_e32 v50, s24, v50
	v_ashrrev_i32_e32 v51, 31, v50
	v_lshlrev_b64 v[50:51], 11, v[50:51]
	v_lshl_add_u64 v[50:51], v[72:73], 0, v[50:51]
	global_store_dword v[50:51], v46, off
	v_or_b32_e32 v46, 1, v52
	v_xad_u32 v50, v52, -2, s12
	v_cndmask_b32_e32 v46, v50, v46, vcc
	v_add_u32_e32 v50, s24, v46
	v_ashrrev_i32_e32 v51, 31, v50
	v_lshlrev_b64 v[50:51], 11, v[50:51]
	v_lshl_add_u64 v[50:51], v[72:73], 0, v[50:51]
	global_store_dword v[50:51], v47, off
	v_or_b32_e32 v46, 2, v52
	v_xad_u32 v47, v52, -3, s12
	v_cndmask_b32_e32 v46, v47, v46, vcc
	v_add_u32_e32 v46, s24, v46
	v_ashrrev_i32_e32 v47, 31, v46
	v_lshlrev_b64 v[46:47], 11, v[46:47]
	v_lshl_add_u64 v[46:47], v[72:73], 0, v[46:47]
	global_store_dword v[46:47], v48, off
	v_or_b32_e32 v46, 3, v52
	v_xad_u32 v47, v52, -4, s12
	v_cndmask_b32_e32 v46, v47, v46, vcc
	v_add_u32_e32 v46, s24, v46
	v_ashrrev_i32_e32 v47, 31, v46
	v_lshlrev_b64 v[46:47], 11, v[46:47]
	v_lshl_add_u64 v[46:47], v[72:73], 0, v[46:47]
	global_store_dword v[46:47], v49, off
	v_not_b32_e32 v47, 16
	v_bitop3_b32 v47, s0, v47, v84 bitop3:0x36
	v_or_b32_e32 v46, 16, v52
	v_add_u32_e32 v47, s12, v47
	v_cndmask_b32_e32 v46, v47, v46, vcc
	v_add_u32_e32 v46, s24, v46
	v_ashrrev_i32_e32 v47, 31, v46
	v_lshlrev_b64 v[46:47], 11, v[46:47]
	v_lshl_add_u64 v[46:47], v[72:73], 0, v[46:47]
	global_store_dword v[46:47], v42, off
	v_not_b32_e32 v46, 17
	v_bitop3_b32 v46, s0, v46, v84 bitop3:0x36
	v_or_b32_e32 v42, 17, v52
	v_add_u32_e32 v46, s12, v46
	v_cndmask_b32_e32 v42, v46, v42, vcc
	v_add_u32_e32 v46, s24, v42
	v_ashrrev_i32_e32 v47, 31, v46
	v_lshlrev_b64 v[46:47], 11, v[46:47]
	v_lshl_add_u64 v[46:47], v[72:73], 0, v[46:47]
	global_store_dword v[46:47], v43, off
	v_not_b32_e32 v43, 18
	v_bitop3_b32 v43, s0, v43, v84 bitop3:0x36
	v_or_b32_e32 v42, 18, v52
	v_add_u32_e32 v43, s12, v43
	v_cndmask_b32_e32 v42, v43, v42, vcc
	v_add_u32_e32 v42, s24, v42
	v_ashrrev_i32_e32 v43, 31, v42
	v_lshlrev_b64 v[42:43], 11, v[42:43]
	v_lshl_add_u64 v[42:43], v[72:73], 0, v[42:43]
	global_store_dword v[42:43], v44, off
	v_not_b32_e32 v43, 19
	v_bitop3_b32 v43, s0, v43, v84 bitop3:0x36
	v_or_b32_e32 v42, 19, v52
	v_add_u32_e32 v43, s12, v43
	v_cndmask_b32_e32 v42, v43, v42, vcc
	v_add_u32_e32 v42, s24, v42
	v_ashrrev_i32_e32 v43, 31, v42
	v_lshlrev_b64 v[42:43], 11, v[42:43]
	v_lshl_add_u64 v[42:43], v[72:73], 0, v[42:43]
	global_store_dword v[42:43], v45, off
	v_not_b32_e32 v43, 32
	v_bitop3_b32 v43, s0, v43, v84 bitop3:0x36
	v_or_b32_e32 v42, 32, v52
	v_add_u32_e32 v43, s12, v43
	v_cndmask_b32_e32 v42, v43, v42, vcc
	v_add_u32_e32 v42, s24, v42
	v_ashrrev_i32_e32 v43, 31, v42
	v_lshlrev_b64 v[42:43], 11, v[42:43]
	v_lshl_add_u64 v[42:43], v[72:73], 0, v[42:43]
	global_store_dword v[42:43], v38, off
	v_not_b32_e32 v42, 33
	v_bitop3_b32 v42, s0, v42, v84 bitop3:0x36
	v_or_b32_e32 v38, 33, v52
	v_add_u32_e32 v42, s12, v42
	v_cndmask_b32_e32 v38, v42, v38, vcc
	v_add_u32_e32 v42, s24, v38
	v_ashrrev_i32_e32 v43, 31, v42
	v_lshlrev_b64 v[42:43], 11, v[42:43]
	v_lshl_add_u64 v[42:43], v[72:73], 0, v[42:43]
	global_store_dword v[42:43], v39, off
	v_not_b32_e32 v39, 34
	v_bitop3_b32 v39, s0, v39, v84 bitop3:0x36
	v_or_b32_e32 v38, 34, v52
	v_add_u32_e32 v39, s12, v39
	v_cndmask_b32_e32 v38, v39, v38, vcc
	v_add_u32_e32 v38, s24, v38
	v_ashrrev_i32_e32 v39, 31, v38
	v_lshlrev_b64 v[38:39], 11, v[38:39]
	v_lshl_add_u64 v[38:39], v[72:73], 0, v[38:39]
	global_store_dword v[38:39], v40, off
	v_not_b32_e32 v39, 35
	v_bitop3_b32 v39, s0, v39, v84 bitop3:0x36
	v_or_b32_e32 v38, 35, v52
	v_add_u32_e32 v39, s12, v39
	v_cndmask_b32_e32 v38, v39, v38, vcc
	v_add_u32_e32 v38, s24, v38
	v_ashrrev_i32_e32 v39, 31, v38
	v_lshlrev_b64 v[38:39], 11, v[38:39]
	v_lshl_add_u64 v[38:39], v[72:73], 0, v[38:39]
	global_store_dword v[38:39], v41, off
	v_not_b32_e32 v39, 48
	v_bitop3_b32 v39, s0, v39, v84 bitop3:0x36
	v_or_b32_e32 v38, 48, v52
	v_add_u32_e32 v39, s12, v39
	v_cndmask_b32_e32 v38, v39, v38, vcc
	v_add_u32_e32 v38, s24, v38
	v_ashrrev_i32_e32 v39, 31, v38
	v_lshlrev_b64 v[38:39], 11, v[38:39]
	v_lshl_add_u64 v[38:39], v[72:73], 0, v[38:39]
	global_store_dword v[38:39], v34, off
	v_not_b32_e32 v38, 49
	v_bitop3_b32 v38, s0, v38, v84 bitop3:0x36
	v_or_b32_e32 v34, 49, v52
	v_add_u32_e32 v38, s12, v38
	v_cndmask_b32_e32 v34, v38, v34, vcc
	v_add_u32_e32 v38, s24, v34
	v_ashrrev_i32_e32 v39, 31, v38
	v_lshlrev_b64 v[38:39], 11, v[38:39]
	v_lshl_add_u64 v[38:39], v[72:73], 0, v[38:39]
	global_store_dword v[38:39], v35, off
	v_not_b32_e32 v35, 50
	v_bitop3_b32 v35, s0, v35, v84 bitop3:0x36
	v_or_b32_e32 v34, 50, v52
	v_add_u32_e32 v35, s12, v35
	v_cndmask_b32_e32 v34, v35, v34, vcc
	v_add_u32_e32 v34, s24, v34
	v_ashrrev_i32_e32 v35, 31, v34
	v_lshlrev_b64 v[34:35], 11, v[34:35]
	v_lshl_add_u64 v[34:35], v[72:73], 0, v[34:35]
	global_store_dword v[34:35], v36, off
	v_not_b32_e32 v35, 51
	v_bitop3_b32 v35, s0, v35, v84 bitop3:0x36
	v_or_b32_e32 v34, 51, v52
	v_add_u32_e32 v35, s12, v35
	v_cndmask_b32_e32 v34, v35, v34, vcc
	v_add_u32_e32 v34, s24, v34
	v_ashrrev_i32_e32 v35, 31, v34
	v_lshlrev_b64 v[34:35], 11, v[34:35]
	v_lshl_add_u64 v[34:35], v[72:73], 0, v[34:35]
	s_andn2_b64 vcc, exec, s[6:7]
	global_store_dword v[34:35], v37, off
	s_cbranch_vccnz .LBB0_1288
	s_lshl_b64 s[6:7], s[8:9], 2
	s_add_u32 s6, s18, s6
	s_addc_u32 s7, s19, s7
	v_lshl_add_u64 v[34:35], v[70:71], 2, s[6:7]
	v_lshl_add_u64 v[34:35], v[34:35], 0, v[0:1]
	global_store_dword v[34:35], v30, off
	global_store_dword v[34:35], v31, off offset:512
	global_store_dword v[34:35], v32, off offset:1024
	global_store_dword v[34:35], v33, off offset:1536
	v_add_co_u32_e32 v30, vcc, s64, v34
	s_movk_i32 s0, 0x6000
	s_nop 0
	v_addc_co_u32_e32 v31, vcc, 0, v35, vcc
	global_store_dword v[30:31], v22, off
	global_store_dword v[30:31], v23, off offset:512
	global_store_dword v[30:31], v24, off offset:1024
	global_store_dword v[30:31], v25, off offset:1536
	v_add_co_u32_e32 v22, vcc, s1, v34
	s_nop 1
	v_addc_co_u32_e32 v23, vcc, 0, v35, vcc
	global_store_dword v[22:23], v26, off
	global_store_dword v[22:23], v27, off offset:512
	global_store_dword v[22:23], v28, off offset:1024
	global_store_dword v[22:23], v29, off offset:1536
	v_add_co_u32_e32 v22, vcc, s0, v34
	s_mov_b32 s0, 0x8000
	s_nop 0
	v_addc_co_u32_e32 v23, vcc, 0, v35, vcc
	global_store_dword v[22:23], v14, off
	global_store_dword v[22:23], v15, off offset:512
	global_store_dword v[22:23], v16, off offset:1024
	global_store_dword v[22:23], v17, off offset:1536
	v_add_co_u32_e32 v14, vcc, s0, v34
	s_mov_b32 s0, 0xa000
	s_nop 0
	v_addc_co_u32_e32 v15, vcc, 0, v35, vcc
	global_store_dword v[14:15], v18, off
	global_store_dword v[14:15], v19, off offset:512
	global_store_dword v[14:15], v20, off offset:1024
	global_store_dword v[14:15], v21, off offset:1536
	v_add_co_u32_e32 v14, vcc, s0, v34
	s_nop 1
	v_addc_co_u32_e32 v15, vcc, 0, v35, vcc
	global_store_dword v[14:15], v6, off
	global_store_dword v[14:15], v7, off offset:512
	global_store_dword v[14:15], v8, off offset:1024
	global_store_dword v[14:15], v9, off offset:1536
	v_add_co_u32_e32 v6, vcc, 0xc000, v34
	s_nop 1
	v_addc_co_u32_e32 v7, vcc, 0, v35, vcc
	global_store_dword v[6:7], v10, off
	global_store_dword v[6:7], v11, off offset:512
	global_store_dword v[6:7], v12, off offset:1024
	global_store_dword v[6:7], v13, off offset:1536
	v_add_co_u32_e32 v6, vcc, 0xe000, v34
	s_nop 1
	v_addc_co_u32_e32 v7, vcc, 0, v35, vcc
	global_store_dword v[6:7], v2, off
	global_store_dword v[6:7], v3, off offset:512
	global_store_dword v[6:7], v4, off offset:1024
	global_store_dword v[6:7], v5, off offset:1536
	s_branch .LBB0_1288
